# v57 + weight-conversion with-gain loops (prep + M3 filler): 8 serialized load/wait/mul/ds_write stages per trip turned into 16 loads in flight then one wait
# speedup vs baseline: 1.0050x; 1.0027x over previous
; __device__ __forceinline__ void cvt_job(const Frame& F, const float* W, int K, int Nsrc, bf16_t* dst, int nrows, int mode, float scale, const float* gain = nullptr) {
;     ...
;     for (int it = F.gw; it < nitems; it += F.NGW) {
;         const int kb = it / nblk, nb = it % nblk, k0 = 64 * kb, n0 = 32 * nb;
;         const int nsrc = map_col(mode, n0 + (lane & 31));
; #pragma unroll 8
;         for (int i = 0; i < 32; ++i) { const int kk = 2 * i + (lane >> 5); scr[kk * 33 + (lane & 31)] = (mode == MAP_ZERO) ? 0.f : W[(size_t)(k0 + kk) * Nsrc + nsrc] * (gain ? scale * gain[k0 + kk] : scale); }
; __device__ __forceinline__ void convert_phase(const Frame& F, int L, int part) {
;     ...
;         cvt_job(F, arg_in(F, 7) + (size_t)j * D * 2048, D, 2048, qkv, 2048, MAP_ID, 1.f, g1);
.LBB0_126:
	s_andn2_b64 vcc, exec, s[48:49]
	s_cbranch_vccnz .Lcvtgp0_ng
	v_add_u32_e32 v96, s13, v8
	v_ashrrev_i32_e32 v97, 31, v96
	v_lshlrev_b64 v[98:99], 13, v[96:97]
	v_lshl_add_u64 v[100:101], v[6:7], 0, v[98:99]
	global_load_dword v152, v[100:101], off
	v_lshl_add_u64 v[102:103], v[96:97], 2, s[22:23]
	global_load_dword v153, v[102:103], off
	v_add_u32_e32 v104, 2, v96
	v_ashrrev_i32_e32 v105, 31, v104
	v_lshlrev_b64 v[106:107], 13, v[104:105]
	v_lshl_add_u64 v[108:109], v[6:7], 0, v[106:107]
	global_load_dword v154, v[108:109], off
	v_lshl_add_u64 v[110:111], s[52:53], 0, v[10:11]
	global_load_dword v155, v[110:111], off offset:-48
	v_add_u32_e32 v112, 4, v96
	v_ashrrev_i32_e32 v113, 31, v112
	v_lshlrev_b64 v[114:115], 13, v[112:113]
	v_lshl_add_u64 v[116:117], v[6:7], 0, v[114:115]
	global_load_dword v156, v[116:117], off
	global_load_dword v157, v[110:111], off offset:-40
	v_add_u32_e32 v118, 6, v96
	v_ashrrev_i32_e32 v119, 31, v118
	v_lshlrev_b64 v[120:121], 13, v[118:119]
	v_lshl_add_u64 v[122:123], v[6:7], 0, v[120:121]
	global_load_dword v158, v[122:123], off
	global_load_dword v159, v[110:111], off offset:-32
	v_add_u32_e32 v124, 8, v96
	v_ashrrev_i32_e32 v125, 31, v124
	v_lshlrev_b64 v[126:127], 13, v[124:125]
	v_lshl_add_u64 v[128:129], v[6:7], 0, v[126:127]
	global_load_dword v160, v[128:129], off
	global_load_dword v161, v[110:111], off offset:-24
	v_add_u32_e32 v130, 10, v96
	v_ashrrev_i32_e32 v131, 31, v130
	v_lshlrev_b64 v[132:133], 13, v[130:131]
	v_lshl_add_u64 v[134:135], v[6:7], 0, v[132:133]
	global_load_dword v162, v[134:135], off
	global_load_dword v163, v[110:111], off offset:-16
	v_add_u32_e32 v136, 12, v96
	v_ashrrev_i32_e32 v137, 31, v136
	v_lshlrev_b64 v[138:139], 13, v[136:137]
	v_lshl_add_u64 v[140:141], v[6:7], 0, v[138:139]
	global_load_dword v164, v[140:141], off
	global_load_dword v165, v[110:111], off offset:-8
	v_add_u32_e32 v142, 14, v96
	v_ashrrev_i32_e32 v143, 31, v142
	v_lshlrev_b64 v[144:145], 13, v[142:143]
	v_lshl_add_u64 v[146:147], v[6:7], 0, v[144:145]
	global_load_dword v166, v[146:147], off
	global_load_dword v167, v[110:111], off
	s_waitcnt vmcnt(0)
	v_cndmask_b32_e64 v15, 0, 1, s[48:49]
	v_mov_b32_e32 v21, 1.0
	v_cmp_ne_u32_e64 s[34:35], 1, v15
	v_mov_b32_e32 v15, 1.0
	v_mul_f32_e32 v14, v152, v153
	ds_write_b32 v9, v14
	v_mul_f32_e32 v13, v154, v155
	ds_write_b32 v9, v13 offset:264
	v_mov_b32_e32 v13, 1.0
	v_mov_b32_e32 v21, 1.0
	v_mul_f32_e32 v21, v156, v157
	ds_write_b32 v9, v21 offset:528
	v_mul_f32_e32 v13, v158, v159
	ds_write_b32 v9, v13 offset:792
	v_mov_b32_e32 v13, 1.0
	v_mov_b32_e32 v23, 1.0
	v_mul_f32_e32 v21, v160, v161
	ds_write_b32 v9, v21 offset:1056
	v_mul_f32_e32 v13, v162, v163
	ds_write_b32 v9, v13 offset:1320
	v_mov_b32_e32 v13, 1.0
	v_mov_b32_e32 v22, 1.0
	v_mul_f32_e32 v21, v164, v165
	ds_write_b32 v9, v21 offset:1584
	s_add_i32 s13, s13, 16
	s_add_u32 s52, s52, 64
	v_mul_f32_e32 v12, v166, v167
	s_addc_u32 s53, s53, 0
	ds_write_b32 v9, v12 offset:1848
	s_cmp_eq_u32 s13, 64
	v_add_u32_e32 v9, 0x840, v9
	s_cbranch_scc1 .LBB0_123
	s_branch .LBB0_126
.Lcvtgp0_ng:
	v_add_u32_e32 v96, s13, v8
	v_ashrrev_i32_e32 v97, 31, v96
	v_lshlrev_b64 v[98:99], 13, v[96:97]
	v_lshl_add_u64 v[100:101], v[6:7], 0, v[98:99]
	global_load_dword v152, v[100:101], off
	v_add_u32_e32 v102, 2, v96
	v_ashrrev_i32_e32 v103, 31, v102
	v_lshlrev_b64 v[104:105], 13, v[102:103]
	v_lshl_add_u64 v[106:107], v[6:7], 0, v[104:105]
	global_load_dword v153, v[106:107], off
	v_add_u32_e32 v108, 4, v96
	v_ashrrev_i32_e32 v109, 31, v108
	v_lshlrev_b64 v[110:111], 13, v[108:109]
	v_lshl_add_u64 v[112:113], v[6:7], 0, v[110:111]
	global_load_dword v154, v[112:113], off
	v_add_u32_e32 v114, 6, v96
	v_ashrrev_i32_e32 v115, 31, v114
	v_lshlrev_b64 v[116:117], 13, v[114:115]
	v_lshl_add_u64 v[118:119], v[6:7], 0, v[116:117]
	global_load_dword v155, v[118:119], off
	v_add_u32_e32 v120, 8, v96
	v_ashrrev_i32_e32 v121, 31, v120
	v_lshlrev_b64 v[122:123], 13, v[120:121]
	v_lshl_add_u64 v[124:125], v[6:7], 0, v[122:123]
	global_load_dword v156, v[124:125], off
	v_add_u32_e32 v126, 10, v96
	v_ashrrev_i32_e32 v127, 31, v126
	v_lshlrev_b64 v[128:129], 13, v[126:127]
	v_lshl_add_u64 v[130:131], v[6:7], 0, v[128:129]
	global_load_dword v157, v[130:131], off
	v_add_u32_e32 v132, 12, v96
	v_ashrrev_i32_e32 v133, 31, v132
	v_lshlrev_b64 v[134:135], 13, v[132:133]
	v_lshl_add_u64 v[136:137], v[6:7], 0, v[134:135]
	global_load_dword v158, v[136:137], off
	v_add_u32_e32 v138, 14, v96
	v_ashrrev_i32_e32 v139, 31, v138
	v_lshlrev_b64 v[140:141], 13, v[138:139]
	v_lshl_add_u64 v[142:143], v[6:7], 0, v[140:141]
	global_load_dword v159, v[142:143], off
	s_waitcnt vmcnt(0)
	v_cndmask_b32_e64 v15, 0, 1, s[48:49]
	v_mov_b32_e32 v21, 1.0
	v_cmp_ne_u32_e64 s[34:35], 1, v15
	v_mov_b32_e32 v15, 1.0
	v_mul_f32_e32 v14, v152, v15
	ds_write_b32 v9, v14
	v_lshl_add_u64 v[14:15], s[52:53], 0, v[10:11]
	v_mul_f32_e32 v13, v153, v21
	ds_write_b32 v9, v13 offset:264
	v_mov_b32_e32 v13, 1.0
	v_mov_b32_e32 v21, 1.0
	v_mul_f32_e32 v21, v154, v21
	ds_write_b32 v9, v21 offset:528
	v_mul_f32_e32 v13, v155, v13
	ds_write_b32 v9, v13 offset:792
	v_mov_b32_e32 v13, 1.0
	v_mov_b32_e32 v23, 1.0
	v_mul_f32_e32 v21, v156, v23
	ds_write_b32 v9, v21 offset:1056
	v_mul_f32_e32 v13, v157, v13
	ds_write_b32 v9, v13 offset:1320
	v_mov_b32_e32 v13, 1.0
	v_mov_b32_e32 v22, 1.0
	v_mul_f32_e32 v21, v158, v22
	ds_write_b32 v9, v21 offset:1584
	s_add_i32 s13, s13, 16
	s_add_u32 s52, s52, 64
	v_mul_f32_e32 v12, v159, v13
	s_addc_u32 s53, s53, 0
	ds_write_b32 v9, v12 offset:1848
	s_cmp_eq_u32 s13, 64
	v_add_u32_e32 v9, 0x840, v9
	s_cbranch_scc1 .LBB0_123
	s_branch .LBB0_126

; __device__ __forceinline__ void cvt_job(const Frame& F, const float* W, int K, int Nsrc, bf16_t* dst, int nrows, int mode, float scale, const float* gain = nullptr) {
;     ...
;     for (int it = F.gw; it < nitems; it += F.NGW) {
;         const int kb = it / nblk, nb = it % nblk, k0 = 64 * kb, n0 = 32 * nb;
;         const int nsrc = map_col(mode, n0 + (lane & 31));
; #pragma unroll 8
;         for (int i = 0; i < 32; ++i) { const int kk = 2 * i + (lane >> 5); scr[kk * 33 + (lane & 31)] = (mode == MAP_ZERO) ? 0.f : W[(size_t)(k0 + kk) * Nsrc + nsrc] * (gain ? scale * gain[k0 + kk] : scale); }
; __device__ __forceinline__ void convert_phase(const Frame& F, int L, int part) {
;     ...
;         cvt_job(F, arg_in(F, 8) + (size_t)j * D * 2048, D, 2048, qkv + (size_t)2048 * D, 2048, MAP_ID, 0.0625f, g1);
.LBB0_147:
	s_andn2_b64 vcc, exec, s[42:43]
	s_cbranch_vccnz .Lcvtgp1_ng
	v_add_u32_e32 v96, s13, v8
	v_ashrrev_i32_e32 v97, 31, v96
	v_lshlrev_b64 v[98:99], 13, v[96:97]
	v_lshl_add_u64 v[100:101], v[6:7], 0, v[98:99]
	global_load_dword v152, v[100:101], off
	v_lshl_add_u64 v[102:103], v[96:97], 2, s[22:23]
	global_load_dword v153, v[102:103], off
	v_add_u32_e32 v104, 2, v96
	v_ashrrev_i32_e32 v105, 31, v104
	v_lshlrev_b64 v[106:107], 13, v[104:105]
	v_lshl_add_u64 v[108:109], v[6:7], 0, v[106:107]
	global_load_dword v154, v[108:109], off
	v_lshl_add_u64 v[110:111], s[48:49], 0, v[10:11]
	global_load_dword v155, v[110:111], off offset:-48
	v_add_u32_e32 v112, 4, v96
	v_ashrrev_i32_e32 v113, 31, v112
	v_lshlrev_b64 v[114:115], 13, v[112:113]
	v_lshl_add_u64 v[116:117], v[6:7], 0, v[114:115]
	global_load_dword v156, v[116:117], off
	global_load_dword v157, v[110:111], off offset:-40
	v_add_u32_e32 v118, 6, v96
	v_ashrrev_i32_e32 v119, 31, v118
	v_lshlrev_b64 v[120:121], 13, v[118:119]
	v_lshl_add_u64 v[122:123], v[6:7], 0, v[120:121]
	global_load_dword v158, v[122:123], off
	global_load_dword v159, v[110:111], off offset:-32
	v_add_u32_e32 v124, 8, v96
	v_ashrrev_i32_e32 v125, 31, v124
	v_lshlrev_b64 v[126:127], 13, v[124:125]
	v_lshl_add_u64 v[128:129], v[6:7], 0, v[126:127]
	global_load_dword v160, v[128:129], off
	global_load_dword v161, v[110:111], off offset:-24
	v_add_u32_e32 v130, 10, v96
	v_ashrrev_i32_e32 v131, 31, v130
	v_lshlrev_b64 v[132:133], 13, v[130:131]
	v_lshl_add_u64 v[134:135], v[6:7], 0, v[132:133]
	global_load_dword v162, v[134:135], off
	global_load_dword v163, v[110:111], off offset:-16
	v_add_u32_e32 v136, 12, v96
	v_ashrrev_i32_e32 v137, 31, v136
	v_lshlrev_b64 v[138:139], 13, v[136:137]
	v_lshl_add_u64 v[140:141], v[6:7], 0, v[138:139]
	global_load_dword v164, v[140:141], off
	global_load_dword v165, v[110:111], off offset:-8
	v_add_u32_e32 v142, 14, v96
	v_ashrrev_i32_e32 v143, 31, v142
	v_lshlrev_b64 v[144:145], 13, v[142:143]
	v_lshl_add_u64 v[146:147], v[6:7], 0, v[144:145]
	global_load_dword v166, v[146:147], off
	global_load_dword v167, v[110:111], off
	s_waitcnt vmcnt(0)
	v_cndmask_b32_e64 v15, 0, 1, s[42:43]
	v_mov_b32_e32 v21, 0x3d800000
	v_cmp_ne_u32_e64 s[34:35], 1, v15
	v_mov_b32_e32 v15, 0x3d800000
	v_mul_f32_e32 v15, 0x3d800000, v153
	v_mul_f32_e32 v14, v152, v15
	ds_write_b32 v9, v14
	v_mul_f32_e32 v21, 0x3d800000, v155
	v_mul_f32_e32 v13, v154, v21
	ds_write_b32 v9, v13 offset:264
	v_mov_b32_e32 v13, 0x3d800000
	v_mov_b32_e32 v21, 0x3d800000
	v_mul_f32_e32 v21, 0x3d800000, v157
	v_mul_f32_e32 v21, v156, v21
	ds_write_b32 v9, v21 offset:528
	v_mul_f32_e32 v13, 0x3d800000, v159
	v_mul_f32_e32 v13, v158, v13
	ds_write_b32 v9, v13 offset:792
	v_mov_b32_e32 v13, 0x3d800000
	v_mov_b32_e32 v23, 0x3d800000
	v_mul_f32_e32 v23, 0x3d800000, v161
	v_mul_f32_e32 v21, v160, v23
	ds_write_b32 v9, v21 offset:1056
	v_mul_f32_e32 v13, 0x3d800000, v163
	v_mul_f32_e32 v13, v162, v13
	ds_write_b32 v9, v13 offset:1320
	v_mov_b32_e32 v13, 0x3d800000
	v_mov_b32_e32 v22, 0x3d800000
	v_mul_f32_e32 v22, 0x3d800000, v165
	v_mul_f32_e32 v21, v164, v22
	ds_write_b32 v9, v21 offset:1584
	v_mul_f32_e32 v13, 0x3d800000, v167
	s_add_i32 s13, s13, 16
	s_add_u32 s48, s48, 64
	v_mul_f32_e32 v12, v166, v13
	s_addc_u32 s49, s49, 0
	ds_write_b32 v9, v12 offset:1848
	s_cmp_eq_u32 s13, 64
	v_add_u32_e32 v9, 0x840, v9
	s_cbranch_scc1 .LBB0_144
	s_branch .LBB0_147
.Lcvtgp1_ng:
	v_add_u32_e32 v96, s13, v8
	v_ashrrev_i32_e32 v97, 31, v96
	v_lshlrev_b64 v[98:99], 13, v[96:97]
	v_lshl_add_u64 v[100:101], v[6:7], 0, v[98:99]
	global_load_dword v152, v[100:101], off
	v_add_u32_e32 v102, 2, v96
	v_ashrrev_i32_e32 v103, 31, v102
	v_lshlrev_b64 v[104:105], 13, v[102:103]
	v_lshl_add_u64 v[106:107], v[6:7], 0, v[104:105]
	global_load_dword v153, v[106:107], off
	v_add_u32_e32 v108, 4, v96
	v_ashrrev_i32_e32 v109, 31, v108
	v_lshlrev_b64 v[110:111], 13, v[108:109]
	v_lshl_add_u64 v[112:113], v[6:7], 0, v[110:111]
	global_load_dword v154, v[112:113], off
	v_add_u32_e32 v114, 6, v96
	v_ashrrev_i32_e32 v115, 31, v114
	v_lshlrev_b64 v[116:117], 13, v[114:115]
	v_lshl_add_u64 v[118:119], v[6:7], 0, v[116:117]
	global_load_dword v155, v[118:119], off
	v_add_u32_e32 v120, 8, v96
	v_ashrrev_i32_e32 v121, 31, v120
	v_lshlrev_b64 v[122:123], 13, v[120:121]
	v_lshl_add_u64 v[124:125], v[6:7], 0, v[122:123]
	global_load_dword v156, v[124:125], off
	v_add_u32_e32 v126, 10, v96
	v_ashrrev_i32_e32 v127, 31, v126
	v_lshlrev_b64 v[128:129], 13, v[126:127]
	v_lshl_add_u64 v[130:131], v[6:7], 0, v[128:129]
	global_load_dword v157, v[130:131], off
	v_add_u32_e32 v132, 12, v96
	v_ashrrev_i32_e32 v133, 31, v132
	v_lshlrev_b64 v[134:135], 13, v[132:133]
	v_lshl_add_u64 v[136:137], v[6:7], 0, v[134:135]
	global_load_dword v158, v[136:137], off
	v_add_u32_e32 v138, 14, v96
	v_ashrrev_i32_e32 v139, 31, v138
	v_lshlrev_b64 v[140:141], 13, v[138:139]
	v_lshl_add_u64 v[142:143], v[6:7], 0, v[140:141]
	global_load_dword v159, v[142:143], off
	s_waitcnt vmcnt(0)
	v_cndmask_b32_e64 v15, 0, 1, s[42:43]
	v_mov_b32_e32 v21, 0x3d800000
	v_cmp_ne_u32_e64 s[34:35], 1, v15
	v_mov_b32_e32 v15, 0x3d800000
	v_mul_f32_e32 v14, v152, v15
	ds_write_b32 v9, v14
	v_lshl_add_u64 v[14:15], s[48:49], 0, v[10:11]
	v_mul_f32_e32 v13, v153, v21
	ds_write_b32 v9, v13 offset:264
	v_mov_b32_e32 v13, 0x3d800000
	v_mov_b32_e32 v21, 0x3d800000
	v_mul_f32_e32 v21, v154, v21
	ds_write_b32 v9, v21 offset:528
	v_mul_f32_e32 v13, v155, v13
	ds_write_b32 v9, v13 offset:792
	v_mov_b32_e32 v13, 0x3d800000
	v_mov_b32_e32 v23, 0x3d800000
	v_mul_f32_e32 v21, v156, v23
	ds_write_b32 v9, v21 offset:1056
	v_mul_f32_e32 v13, v157, v13
	ds_write_b32 v9, v13 offset:1320
	v_mov_b32_e32 v13, 0x3d800000
	v_mov_b32_e32 v22, 0x3d800000
	v_mul_f32_e32 v21, v158, v22
	ds_write_b32 v9, v21 offset:1584
	s_add_i32 s13, s13, 16
	s_add_u32 s48, s48, 64
	v_mul_f32_e32 v12, v159, v13
	s_addc_u32 s49, s49, 0
	ds_write_b32 v9, v12 offset:1848
	s_cmp_eq_u32 s13, 64
	v_add_u32_e32 v9, 0x840, v9
	s_cbranch_scc1 .LBB0_144
	s_branch .LBB0_147

; __device__ __forceinline__ void cvt_job(const Frame& F, const float* W, int K, int Nsrc, bf16_t* dst, int nrows, int mode, float scale, const float* gain = nullptr) {
;     ...
;     for (int it = F.gw; it < nitems; it += F.NGW) {
;         const int kb = it / nblk, nb = it % nblk, k0 = 64 * kb, n0 = 32 * nb;
;         const int nsrc = map_col(mode, n0 + (lane & 31));
; #pragma unroll 8
;         for (int i = 0; i < 32; ++i) { const int kk = 2 * i + (lane >> 5); scr[kk * 33 + (lane & 31)] = (mode == MAP_ZERO) ? 0.f : W[(size_t)(k0 + kk) * Nsrc + nsrc] * (gain ? scale * gain[k0 + kk] : scale); }
; __device__ __forceinline__ void convert_phase(const Frame& F, int L, int part) {
;     ...
;         cvt_job(F, arg_in(F, 9) + (size_t)j * D * 4096, D, 4096, qkv + (size_t)4096 * D, 4096, MAP_ID, 1.f, g1);
.LBB0_168:
	s_andn2_b64 vcc, exec, s[42:43]
	s_cbranch_vccnz .Lcvtgp2_ng
	v_lshl_add_u64 v[96:97], v[8:9], 0, s[50:51]
	global_load_dword v152, v[96:97], off
	global_load_dword v153, v[12:13], off
	v_lshl_add_u64 v[98:99], v[22:23], 0, s[50:51]
	global_load_dword v154, v[98:99], off
	global_load_dword v155, v[12:13], off offset:8
	v_lshl_add_u64 v[100:101], v[20:21], 0, s[50:51]
	global_load_dword v156, v[100:101], off
	global_load_dword v157, v[12:13], off offset:16
	v_lshl_add_u64 v[102:103], v[18:19], 0, s[50:51]
	global_load_dword v158, v[102:103], off
	global_load_dword v159, v[12:13], off offset:24
	v_lshl_add_u64 v[104:105], v[16:17], 0, s[50:51]
	global_load_dword v160, v[104:105], off
	global_load_dword v161, v[12:13], off offset:32
	v_lshl_add_u64 v[106:107], v[14:15], 0, s[50:51]
	global_load_dword v162, v[106:107], off
	global_load_dword v163, v[12:13], off offset:40
	v_lshl_add_u64 v[108:109], v[10:11], 0, s[50:51]
	global_load_dword v164, v[108:109], off
	global_load_dword v165, v[12:13], off offset:48
	v_lshl_add_u64 v[110:111], v[6:7], 0, s[50:51]
	global_load_dword v166, v[110:111], off
	global_load_dword v167, v[12:13], off offset:56
	s_waitcnt vmcnt(0)
	v_cndmask_b32_e64 v41, 0, 1, s[42:43]
	v_mov_b32_e32 v39, 1.0
	v_cmp_ne_u32_e64 s[34:35], 1, v41
	v_mov_b32_e32 v42, 1.0
	v_mul_f32_e32 v40, v152, v153
	ds_write_b32 v38, v40
	v_mul_f32_e32 v39, v154, v155
	ds_write_b32 v38, v39 offset:264
	v_mov_b32_e32 v39, 1.0
	v_mov_b32_e32 v42, 1.0
	v_mul_f32_e32 v40, v156, v157
	ds_write_b32 v38, v40 offset:528
	v_mul_f32_e32 v39, v158, v159
	ds_write_b32 v38, v39 offset:792
	v_mov_b32_e32 v39, 1.0
	v_mov_b32_e32 v42, 1.0
	v_mul_f32_e32 v40, v160, v161
	ds_write_b32 v38, v40 offset:1056
	v_mul_f32_e32 v39, v162, v163
	ds_write_b32 v38, v39 offset:1320
	v_mov_b32_e32 v39, 1.0
	v_mov_b32_e32 v42, 1.0
	v_mul_f32_e32 v40, v164, v165
	ds_write_b32 v38, v40 offset:1584
	s_add_u32 s50, s50, 0x40000
	v_mul_f32_e32 v39, v166, v167
	s_addc_u32 s51, s51, 0
	ds_write_b32 v38, v39 offset:1848
	v_add_u32_e32 v38, 0x840, v38
	s_cmp_eq_u32 s50, 0x100000
	v_lshl_add_u64 v[12:13], v[12:13], 0, 64
	s_cbranch_scc1 .LBB0_165
	s_branch .LBB0_168
.Lcvtgp2_ng:
	v_lshl_add_u64 v[96:97], v[8:9], 0, s[50:51]
	global_load_dword v152, v[96:97], off
	v_lshl_add_u64 v[98:99], v[22:23], 0, s[50:51]
	global_load_dword v153, v[98:99], off
	v_lshl_add_u64 v[100:101], v[20:21], 0, s[50:51]
	global_load_dword v154, v[100:101], off
	v_lshl_add_u64 v[102:103], v[18:19], 0, s[50:51]
	global_load_dword v155, v[102:103], off
	v_lshl_add_u64 v[104:105], v[16:17], 0, s[50:51]
	global_load_dword v156, v[104:105], off
	v_lshl_add_u64 v[106:107], v[14:15], 0, s[50:51]
	global_load_dword v157, v[106:107], off
	v_lshl_add_u64 v[108:109], v[10:11], 0, s[50:51]
	global_load_dword v158, v[108:109], off
	v_lshl_add_u64 v[110:111], v[6:7], 0, s[50:51]
	global_load_dword v159, v[110:111], off
	s_waitcnt vmcnt(0)
	v_cndmask_b32_e64 v41, 0, 1, s[42:43]
	v_mov_b32_e32 v39, 1.0
	v_cmp_ne_u32_e64 s[34:35], 1, v41
	v_mov_b32_e32 v42, 1.0
	v_mul_f32_e32 v40, v152, v42
	ds_write_b32 v38, v40
	v_mul_f32_e32 v39, v153, v39
	ds_write_b32 v38, v39 offset:264
	v_mov_b32_e32 v39, 1.0
	v_mov_b32_e32 v42, 1.0
	v_mul_f32_e32 v40, v154, v42
	ds_write_b32 v38, v40 offset:528
	v_mul_f32_e32 v39, v155, v39
	ds_write_b32 v38, v39 offset:792
	v_mov_b32_e32 v39, 1.0
	v_mov_b32_e32 v42, 1.0
	v_mul_f32_e32 v40, v156, v42
	ds_write_b32 v38, v40 offset:1056
	v_mul_f32_e32 v39, v157, v39
	ds_write_b32 v38, v39 offset:1320
	v_mov_b32_e32 v39, 1.0
	v_mov_b32_e32 v42, 1.0
	v_mul_f32_e32 v40, v158, v42
	ds_write_b32 v38, v40 offset:1584
	s_add_u32 s50, s50, 0x40000
	v_mul_f32_e32 v39, v159, v39
	s_addc_u32 s51, s51, 0
	ds_write_b32 v38, v39 offset:1848
	v_add_u32_e32 v38, 0x840, v38
	s_cmp_eq_u32 s50, 0x100000
	v_lshl_add_u64 v[12:13], v[12:13], 0, 64
	s_cbranch_scc1 .LBB0_165
	s_branch .LBB0_168

; __device__ __forceinline__ void cvt_job(const Frame& F, const float* W, int K, int Nsrc, bf16_t* dst, int nrows, int mode, float scale, const float* gain = nullptr) {
;     ...
;     for (int it = F.gw; it < nitems; it += F.NGW) {
;         const int kb = it / nblk, nb = it % nblk, k0 = 64 * kb, n0 = 32 * nb;
;         const int nsrc = map_col(mode, n0 + (lane & 31));
; #pragma unroll 8
;         for (int i = 0; i < 32; ++i) { const int kk = 2 * i + (lane >> 5); scr[kk * 33 + (lane & 31)] = (mode == MAP_ZERO) ? 0.f : W[(size_t)(k0 + kk) * Nsrc + nsrc] * (gain ? scale * gain[k0 + kk] : scale); }
; __device__ __forceinline__ void convert_phase(const Frame& F, int L, int part) {
;     ...
;         cvt_job(F, arg_in(F, 10) + (size_t)j * D * 4096, D, 4096, (bf16_t*)(wr + W_RG), 4096, MAP_ID, 1.f, g1);
.LBB0_189:
	s_andn2_b64 vcc, exec, s[30:31]
	s_cbranch_vccnz .Lcvtgp3_ng
	v_lshl_add_u64 v[96:97], v[8:9], 0, s[46:47]
	global_load_dword v152, v[96:97], off
	global_load_dword v153, v[12:13], off
	v_lshl_add_u64 v[98:99], v[22:23], 0, s[46:47]
	global_load_dword v154, v[98:99], off
	global_load_dword v155, v[12:13], off offset:8
	v_lshl_add_u64 v[100:101], v[20:21], 0, s[46:47]
	global_load_dword v156, v[100:101], off
	global_load_dword v157, v[12:13], off offset:16
	v_lshl_add_u64 v[102:103], v[18:19], 0, s[46:47]
	global_load_dword v158, v[102:103], off
	global_load_dword v159, v[12:13], off offset:24
	v_lshl_add_u64 v[104:105], v[16:17], 0, s[46:47]
	global_load_dword v160, v[104:105], off
	global_load_dword v161, v[12:13], off offset:32
	v_lshl_add_u64 v[106:107], v[14:15], 0, s[46:47]
	global_load_dword v162, v[106:107], off
	global_load_dword v163, v[12:13], off offset:40
	v_lshl_add_u64 v[108:109], v[10:11], 0, s[46:47]
	global_load_dword v164, v[108:109], off
	global_load_dword v165, v[12:13], off offset:48
	v_lshl_add_u64 v[110:111], v[6:7], 0, s[46:47]
	global_load_dword v166, v[110:111], off
	global_load_dword v167, v[12:13], off offset:56
	s_waitcnt vmcnt(0)
	v_cndmask_b32_e64 v41, 0, 1, s[30:31]
	v_mov_b32_e32 v39, 1.0
	v_cmp_ne_u32_e64 s[36:37], 1, v41
	v_mov_b32_e32 v42, 1.0
	v_mul_f32_e32 v40, v152, v153
	ds_write_b32 v38, v40
	v_mul_f32_e32 v39, v154, v155
	ds_write_b32 v38, v39 offset:264
	v_mov_b32_e32 v39, 1.0
	v_mov_b32_e32 v42, 1.0
	v_mul_f32_e32 v40, v156, v157
	ds_write_b32 v38, v40 offset:528
	v_mul_f32_e32 v39, v158, v159
	ds_write_b32 v38, v39 offset:792
	v_mov_b32_e32 v39, 1.0
	v_mov_b32_e32 v42, 1.0
	v_mul_f32_e32 v40, v160, v161
	ds_write_b32 v38, v40 offset:1056
	v_mul_f32_e32 v39, v162, v163
	ds_write_b32 v38, v39 offset:1320
	v_mov_b32_e32 v39, 1.0
	v_mov_b32_e32 v42, 1.0
	v_mul_f32_e32 v40, v164, v165
	ds_write_b32 v38, v40 offset:1584
	s_add_u32 s46, s46, 0x40000
	v_mul_f32_e32 v39, v166, v167
	s_addc_u32 s47, s47, 0
	ds_write_b32 v38, v39 offset:1848
	v_add_u32_e32 v38, 0x840, v38
	s_cmp_eq_u32 s46, 0x100000
	v_lshl_add_u64 v[12:13], v[12:13], 0, 64
	s_cbranch_scc1 .LBB0_186
	s_branch .LBB0_189
.Lcvtgp3_ng:
	v_lshl_add_u64 v[96:97], v[8:9], 0, s[46:47]
	global_load_dword v152, v[96:97], off
	v_lshl_add_u64 v[98:99], v[22:23], 0, s[46:47]
	global_load_dword v153, v[98:99], off
	v_lshl_add_u64 v[100:101], v[20:21], 0, s[46:47]
	global_load_dword v154, v[100:101], off
	v_lshl_add_u64 v[102:103], v[18:19], 0, s[46:47]
	global_load_dword v155, v[102:103], off
	v_lshl_add_u64 v[104:105], v[16:17], 0, s[46:47]
	global_load_dword v156, v[104:105], off
	v_lshl_add_u64 v[106:107], v[14:15], 0, s[46:47]
	global_load_dword v157, v[106:107], off
	v_lshl_add_u64 v[108:109], v[10:11], 0, s[46:47]
	global_load_dword v158, v[108:109], off
	v_lshl_add_u64 v[110:111], v[6:7], 0, s[46:47]
	global_load_dword v159, v[110:111], off
	s_waitcnt vmcnt(0)
	v_cndmask_b32_e64 v41, 0, 1, s[30:31]
	v_mov_b32_e32 v39, 1.0
	v_cmp_ne_u32_e64 s[36:37], 1, v41
	v_mov_b32_e32 v42, 1.0
	v_mul_f32_e32 v40, v152, v42
	ds_write_b32 v38, v40
	v_mul_f32_e32 v39, v153, v39
	ds_write_b32 v38, v39 offset:264
	v_mov_b32_e32 v39, 1.0
	v_mov_b32_e32 v42, 1.0
	v_mul_f32_e32 v40, v154, v42
	ds_write_b32 v38, v40 offset:528
	v_mul_f32_e32 v39, v155, v39
	ds_write_b32 v38, v39 offset:792
	v_mov_b32_e32 v39, 1.0
	v_mov_b32_e32 v42, 1.0
	v_mul_f32_e32 v40, v156, v42
	ds_write_b32 v38, v40 offset:1056
	v_mul_f32_e32 v39, v157, v39
	ds_write_b32 v38, v39 offset:1320
	v_mov_b32_e32 v39, 1.0
	v_mov_b32_e32 v42, 1.0
	v_mul_f32_e32 v40, v158, v42
	ds_write_b32 v38, v40 offset:1584
	s_add_u32 s46, s46, 0x40000
	v_mul_f32_e32 v39, v159, v39
	s_addc_u32 s47, s47, 0
	ds_write_b32 v38, v39 offset:1848
	v_add_u32_e32 v38, 0x840, v38
	s_cmp_eq_u32 s46, 0x100000
	v_lshl_add_u64 v[12:13], v[12:13], 0, 64
	s_cbranch_scc1 .LBB0_186
	s_branch .LBB0_189

; __device__ __forceinline__ void cvt_job(const Frame& F, const float* W, int K, int Nsrc, bf16_t* dst, int nrows, int mode, float scale, const float* gain = nullptr) {
;     ...
;     for (int it = F.gw; it < nitems; it += F.NGW) {
;         const int kb = it / nblk, nb = it % nblk, k0 = 64 * kb, n0 = 32 * nb;
;         const int nsrc = map_col(mode, n0 + (lane & 31));
; #pragma unroll 8
;         for (int i = 0; i < 32; ++i) { const int kk = 2 * i + (lane >> 5); scr[kk * 33 + (lane & 31)] = (mode == MAP_ZERO) ? 0.f : W[(size_t)(k0 + kk) * Nsrc + nsrc] * (gain ? scale * gain[k0 + kk] : scale); }
; __device__ __forceinline__ void convert_phase(const Frame& F, int L, int part) {
;     ...
;         cvt_job(F, arg_in(F, 7) + (size_t)j * D * 2048, D, 2048, qkv, 2048, MAP_ID, 1.f, g1);
.LBB0_1647:
	s_andn2_b64 vcc, exec, s[36:37]
	s_cbranch_vccnz .Lcvtgm0_ng
	v_add_u32_e32 v96, s12, v6
	v_ashrrev_i32_e32 v97, 31, v96
	v_lshlrev_b64 v[98:99], 13, v[96:97]
	v_lshl_add_u64 v[100:101], v[4:5], 0, v[98:99]
	global_load_dword v152, v[100:101], off
	v_lshl_add_u64 v[102:103], v[96:97], 2, s[40:41]
	global_load_dword v153, v[102:103], off
	v_add_u32_e32 v104, 2, v96
	v_ashrrev_i32_e32 v105, 31, v104
	v_lshlrev_b64 v[106:107], 13, v[104:105]
	v_lshl_add_u64 v[108:109], v[4:5], 0, v[106:107]
	global_load_dword v154, v[108:109], off
	global_load_dword v155, v[8:9], off offset:-24
	v_add_u32_e32 v110, 4, v96
	v_ashrrev_i32_e32 v111, 31, v110
	v_lshlrev_b64 v[112:113], 13, v[110:111]
	v_lshl_add_u64 v[114:115], v[4:5], 0, v[112:113]
	global_load_dword v156, v[114:115], off
	global_load_dword v157, v[8:9], off offset:-16
	v_add_u32_e32 v116, 6, v96
	v_ashrrev_i32_e32 v117, 31, v116
	v_lshlrev_b64 v[118:119], 13, v[116:117]
	v_lshl_add_u64 v[120:121], v[4:5], 0, v[118:119]
	global_load_dword v158, v[120:121], off
	global_load_dword v159, v[8:9], off offset:-8
	v_add_u32_e32 v122, 8, v96
	v_ashrrev_i32_e32 v123, 31, v122
	v_lshlrev_b64 v[124:125], 13, v[122:123]
	v_lshl_add_u64 v[126:127], v[4:5], 0, v[124:125]
	global_load_dword v160, v[126:127], off
	global_load_dword v161, v[8:9], off
	v_add_u32_e32 v128, 10, v96
	v_ashrrev_i32_e32 v129, 31, v128
	v_lshlrev_b64 v[130:131], 13, v[128:129]
	v_lshl_add_u64 v[132:133], v[4:5], 0, v[130:131]
	global_load_dword v162, v[132:133], off
	global_load_dword v163, v[8:9], off offset:8
	v_add_u32_e32 v134, 12, v96
	v_ashrrev_i32_e32 v135, 31, v134
	v_lshlrev_b64 v[136:137], 13, v[134:135]
	v_lshl_add_u64 v[138:139], v[4:5], 0, v[136:137]
	global_load_dword v164, v[138:139], off
	global_load_dword v165, v[8:9], off offset:16
	v_add_u32_e32 v140, 14, v96
	v_ashrrev_i32_e32 v141, 31, v140
	v_lshlrev_b64 v[142:143], 13, v[140:141]
	v_lshl_add_u64 v[144:145], v[4:5], 0, v[142:143]
	global_load_dword v166, v[144:145], off
	global_load_dword v167, v[8:9], off offset:24
	s_waitcnt vmcnt(0)
	v_cndmask_b32_e64 v20, 0, 1, s[36:37]
	v_mov_b32_e32 v18, 1.0
	v_cmp_ne_u32_e64 s[34:35], 1, v20
	v_mov_b32_e32 v20, 1.0
	v_mul_f32_e32 v11, v152, v153
	ds_write_b32 v7, v11
	v_mul_f32_e32 v11, v154, v155
	ds_write_b32 v7, v11 offset:264
	v_mov_b32_e32 v11, 1.0
	v_mov_b32_e32 v19, 1.0
	v_mul_f32_e32 v18, v156, v157
	ds_write_b32 v7, v18 offset:528
	v_mul_f32_e32 v11, v158, v159
	ds_write_b32 v7, v11 offset:792
	v_mov_b32_e32 v11, 1.0
	v_mov_b32_e32 v19, 1.0
	v_mul_f32_e32 v18, v160, v161
	ds_write_b32 v7, v18 offset:1056
	v_mul_f32_e32 v11, v162, v163
	ds_write_b32 v7, v11 offset:1320
	v_mov_b32_e32 v11, 1.0
	v_mov_b32_e32 v19, 1.0
	v_mul_f32_e32 v18, v164, v165
	ds_write_b32 v7, v18 offset:1584
	v_mul_f32_e32 v10, v166, v167
	s_add_i32 s12, s12, 16
	ds_write_b32 v7, v10 offset:1848
	v_add_u32_e32 v7, 0x840, v7
	s_cmp_eq_u32 s12, 64
	v_lshl_add_u64 v[8:9], v[8:9], 0, 64
	s_cbranch_scc1 .LBB0_1644
	s_branch .LBB0_1647
.Lcvtgm0_ng:
	v_add_u32_e32 v96, s12, v6
	v_ashrrev_i32_e32 v97, 31, v96
	v_lshlrev_b64 v[98:99], 13, v[96:97]
	v_lshl_add_u64 v[100:101], v[4:5], 0, v[98:99]
	global_load_dword v152, v[100:101], off
	v_add_u32_e32 v102, 2, v96
	v_ashrrev_i32_e32 v103, 31, v102
	v_lshlrev_b64 v[104:105], 13, v[102:103]
	v_lshl_add_u64 v[106:107], v[4:5], 0, v[104:105]
	global_load_dword v153, v[106:107], off
	v_add_u32_e32 v108, 4, v96
	v_ashrrev_i32_e32 v109, 31, v108
	v_lshlrev_b64 v[110:111], 13, v[108:109]
	v_lshl_add_u64 v[112:113], v[4:5], 0, v[110:111]
	global_load_dword v154, v[112:113], off
	v_add_u32_e32 v114, 6, v96
	v_ashrrev_i32_e32 v115, 31, v114
	v_lshlrev_b64 v[116:117], 13, v[114:115]
	v_lshl_add_u64 v[118:119], v[4:5], 0, v[116:117]
	global_load_dword v155, v[118:119], off
	v_add_u32_e32 v120, 8, v96
	v_ashrrev_i32_e32 v121, 31, v120
	v_lshlrev_b64 v[122:123], 13, v[120:121]
	v_lshl_add_u64 v[124:125], v[4:5], 0, v[122:123]
	global_load_dword v156, v[124:125], off
	v_add_u32_e32 v126, 10, v96
	v_ashrrev_i32_e32 v127, 31, v126
	v_lshlrev_b64 v[128:129], 13, v[126:127]
	v_lshl_add_u64 v[130:131], v[4:5], 0, v[128:129]
	global_load_dword v157, v[130:131], off
	v_add_u32_e32 v132, 12, v96
	v_ashrrev_i32_e32 v133, 31, v132
	v_lshlrev_b64 v[134:135], 13, v[132:133]
	v_lshl_add_u64 v[136:137], v[4:5], 0, v[134:135]
	global_load_dword v158, v[136:137], off
	v_add_u32_e32 v138, 14, v96
	v_ashrrev_i32_e32 v139, 31, v138
	v_lshlrev_b64 v[140:141], 13, v[138:139]
	v_lshl_add_u64 v[142:143], v[4:5], 0, v[140:141]
	global_load_dword v159, v[142:143], off
	s_waitcnt vmcnt(0)
	v_cndmask_b32_e64 v20, 0, 1, s[36:37]
	v_mov_b32_e32 v18, 1.0
	v_cmp_ne_u32_e64 s[34:35], 1, v20
	v_mov_b32_e32 v20, 1.0
	v_mul_f32_e32 v11, v152, v20
	ds_write_b32 v7, v11
	v_mul_f32_e32 v11, v153, v18
	ds_write_b32 v7, v11 offset:264
	v_mov_b32_e32 v11, 1.0
	v_mov_b32_e32 v19, 1.0
	v_mul_f32_e32 v18, v154, v19
	ds_write_b32 v7, v18 offset:528
	v_mul_f32_e32 v11, v155, v11
	ds_write_b32 v7, v11 offset:792
	v_mov_b32_e32 v11, 1.0
	v_mov_b32_e32 v19, 1.0
	v_mul_f32_e32 v18, v156, v19
	ds_write_b32 v7, v18 offset:1056
	v_mul_f32_e32 v11, v157, v11
	ds_write_b32 v7, v11 offset:1320
	v_mov_b32_e32 v11, 1.0
	v_mov_b32_e32 v19, 1.0
	v_mul_f32_e32 v18, v158, v19
	ds_write_b32 v7, v18 offset:1584
	v_mul_f32_e32 v10, v159, v11
	s_add_i32 s12, s12, 16
	ds_write_b32 v7, v10 offset:1848
	v_add_u32_e32 v7, 0x840, v7
	s_cmp_eq_u32 s12, 64
	v_lshl_add_u64 v[8:9], v[8:9], 0, 64
	s_cbranch_scc1 .LBB0_1644
	s_branch .LBB0_1647

; __device__ __forceinline__ void cvt_job(const Frame& F, const float* W, int K, int Nsrc, bf16_t* dst, int nrows, int mode, float scale, const float* gain = nullptr) {
;     ...
;     for (int it = F.gw; it < nitems; it += F.NGW) {
;         const int kb = it / nblk, nb = it % nblk, k0 = 64 * kb, n0 = 32 * nb;
;         const int nsrc = map_col(mode, n0 + (lane & 31));
; #pragma unroll 8
;         for (int i = 0; i < 32; ++i) { const int kk = 2 * i + (lane >> 5); scr[kk * 33 + (lane & 31)] = (mode == MAP_ZERO) ? 0.f : W[(size_t)(k0 + kk) * Nsrc + nsrc] * (gain ? scale * gain[k0 + kk] : scale); }
; __device__ __forceinline__ void convert_phase(const Frame& F, int L, int part) {
;     ...
;         cvt_job(F, arg_in(F, 8) + (size_t)j * D * 2048, D, 2048, qkv + (size_t)2048 * D, 2048, MAP_ID, 0.0625f, g1);
.LBB0_1668:
	s_andn2_b64 vcc, exec, s[30:31]
	s_cbranch_vccnz .Lcvtgm1_ng
	v_add_u32_e32 v96, s12, v6
	v_ashrrev_i32_e32 v97, 31, v96
	v_lshlrev_b64 v[98:99], 13, v[96:97]
	v_lshl_add_u64 v[100:101], v[4:5], 0, v[98:99]
	global_load_dword v152, v[100:101], off
	v_lshl_add_u64 v[102:103], v[96:97], 2, s[40:41]
	global_load_dword v153, v[102:103], off
	v_add_u32_e32 v104, 2, v96
	v_ashrrev_i32_e32 v105, 31, v104
	v_lshlrev_b64 v[106:107], 13, v[104:105]
	v_lshl_add_u64 v[108:109], v[4:5], 0, v[106:107]
	global_load_dword v154, v[108:109], off
	global_load_dword v155, v[8:9], off offset:-24
	v_add_u32_e32 v110, 4, v96
	v_ashrrev_i32_e32 v111, 31, v110
	v_lshlrev_b64 v[112:113], 13, v[110:111]
	v_lshl_add_u64 v[114:115], v[4:5], 0, v[112:113]
	global_load_dword v156, v[114:115], off
	global_load_dword v157, v[8:9], off offset:-16
	v_add_u32_e32 v116, 6, v96
	v_ashrrev_i32_e32 v117, 31, v116
	v_lshlrev_b64 v[118:119], 13, v[116:117]
	v_lshl_add_u64 v[120:121], v[4:5], 0, v[118:119]
	global_load_dword v158, v[120:121], off
	global_load_dword v159, v[8:9], off offset:-8
	v_add_u32_e32 v122, 8, v96
	v_ashrrev_i32_e32 v123, 31, v122
	v_lshlrev_b64 v[124:125], 13, v[122:123]
	v_lshl_add_u64 v[126:127], v[4:5], 0, v[124:125]
	global_load_dword v160, v[126:127], off
	global_load_dword v161, v[8:9], off
	v_add_u32_e32 v128, 10, v96
	v_ashrrev_i32_e32 v129, 31, v128
	v_lshlrev_b64 v[130:131], 13, v[128:129]
	v_lshl_add_u64 v[132:133], v[4:5], 0, v[130:131]
	global_load_dword v162, v[132:133], off
	global_load_dword v163, v[8:9], off offset:8
	v_add_u32_e32 v134, 12, v96
	v_ashrrev_i32_e32 v135, 31, v134
	v_lshlrev_b64 v[136:137], 13, v[134:135]
	v_lshl_add_u64 v[138:139], v[4:5], 0, v[136:137]
	global_load_dword v164, v[138:139], off
	global_load_dword v165, v[8:9], off offset:16
	v_add_u32_e32 v140, 14, v96
	v_ashrrev_i32_e32 v141, 31, v140
	v_lshlrev_b64 v[142:143], 13, v[140:141]
	v_lshl_add_u64 v[144:145], v[4:5], 0, v[142:143]
	global_load_dword v166, v[144:145], off
	global_load_dword v167, v[8:9], off offset:24
	s_waitcnt vmcnt(0)
	v_cndmask_b32_e64 v20, 0, 1, s[30:31]
	v_mov_b32_e32 v18, 0x3d800000
	v_cmp_ne_u32_e64 s[34:35], 1, v20
	v_mov_b32_e32 v20, 0x3d800000
	v_mul_f32_e32 v20, 0x3d800000, v153
	v_mul_f32_e32 v11, v152, v20
	ds_write_b32 v7, v11
	v_mul_f32_e32 v18, 0x3d800000, v155
	v_mul_f32_e32 v11, v154, v18
	ds_write_b32 v7, v11 offset:264
	v_mov_b32_e32 v11, 0x3d800000
	v_mov_b32_e32 v19, 0x3d800000
	v_mul_f32_e32 v19, 0x3d800000, v157
	v_mul_f32_e32 v18, v156, v19
	ds_write_b32 v7, v18 offset:528
	v_mul_f32_e32 v11, 0x3d800000, v159
	v_mul_f32_e32 v11, v158, v11
	ds_write_b32 v7, v11 offset:792
	v_mov_b32_e32 v11, 0x3d800000
	v_mov_b32_e32 v19, 0x3d800000
	v_mul_f32_e32 v19, 0x3d800000, v161
	v_mul_f32_e32 v18, v160, v19
	ds_write_b32 v7, v18 offset:1056
	v_mul_f32_e32 v11, 0x3d800000, v163
	v_mul_f32_e32 v11, v162, v11
	ds_write_b32 v7, v11 offset:1320
	v_mov_b32_e32 v11, 0x3d800000
	v_mov_b32_e32 v19, 0x3d800000
	v_mul_f32_e32 v19, 0x3d800000, v165
	v_mul_f32_e32 v18, v164, v19
	ds_write_b32 v7, v18 offset:1584
	v_mul_f32_e32 v11, 0x3d800000, v167
	v_mul_f32_e32 v10, v166, v11
	s_add_i32 s12, s12, 16
	ds_write_b32 v7, v10 offset:1848
	v_add_u32_e32 v7, 0x840, v7
	s_cmp_eq_u32 s12, 64
	v_lshl_add_u64 v[8:9], v[8:9], 0, 64
	s_cbranch_scc1 .LBB0_1665
	s_branch .LBB0_1668
.Lcvtgm1_ng:
	v_add_u32_e32 v96, s12, v6
	v_ashrrev_i32_e32 v97, 31, v96
	v_lshlrev_b64 v[98:99], 13, v[96:97]
	v_lshl_add_u64 v[100:101], v[4:5], 0, v[98:99]
	global_load_dword v152, v[100:101], off
	v_add_u32_e32 v102, 2, v96
	v_ashrrev_i32_e32 v103, 31, v102
	v_lshlrev_b64 v[104:105], 13, v[102:103]
	v_lshl_add_u64 v[106:107], v[4:5], 0, v[104:105]
	global_load_dword v153, v[106:107], off
	v_add_u32_e32 v108, 4, v96
	v_ashrrev_i32_e32 v109, 31, v108
	v_lshlrev_b64 v[110:111], 13, v[108:109]
	v_lshl_add_u64 v[112:113], v[4:5], 0, v[110:111]
	global_load_dword v154, v[112:113], off
	v_add_u32_e32 v114, 6, v96
	v_ashrrev_i32_e32 v115, 31, v114
	v_lshlrev_b64 v[116:117], 13, v[114:115]
	v_lshl_add_u64 v[118:119], v[4:5], 0, v[116:117]
	global_load_dword v155, v[118:119], off
	v_add_u32_e32 v120, 8, v96
	v_ashrrev_i32_e32 v121, 31, v120
	v_lshlrev_b64 v[122:123], 13, v[120:121]
	v_lshl_add_u64 v[124:125], v[4:5], 0, v[122:123]
	global_load_dword v156, v[124:125], off
	v_add_u32_e32 v126, 10, v96
	v_ashrrev_i32_e32 v127, 31, v126
	v_lshlrev_b64 v[128:129], 13, v[126:127]
	v_lshl_add_u64 v[130:131], v[4:5], 0, v[128:129]
	global_load_dword v157, v[130:131], off
	v_add_u32_e32 v132, 12, v96
	v_ashrrev_i32_e32 v133, 31, v132
	v_lshlrev_b64 v[134:135], 13, v[132:133]
	v_lshl_add_u64 v[136:137], v[4:5], 0, v[134:135]
	global_load_dword v158, v[136:137], off
	v_add_u32_e32 v138, 14, v96
	v_ashrrev_i32_e32 v139, 31, v138
	v_lshlrev_b64 v[140:141], 13, v[138:139]
	v_lshl_add_u64 v[142:143], v[4:5], 0, v[140:141]
	global_load_dword v159, v[142:143], off
	s_waitcnt vmcnt(0)
	v_cndmask_b32_e64 v20, 0, 1, s[30:31]
	v_mov_b32_e32 v18, 0x3d800000
	v_cmp_ne_u32_e64 s[34:35], 1, v20
	v_mov_b32_e32 v20, 0x3d800000
	v_mul_f32_e32 v11, v152, v20
	ds_write_b32 v7, v11
	v_mul_f32_e32 v11, v153, v18
	ds_write_b32 v7, v11 offset:264
	v_mov_b32_e32 v11, 0x3d800000
	v_mov_b32_e32 v19, 0x3d800000
	v_mul_f32_e32 v18, v154, v19
	ds_write_b32 v7, v18 offset:528
	v_mul_f32_e32 v11, v155, v11
	ds_write_b32 v7, v11 offset:792
	v_mov_b32_e32 v11, 0x3d800000
	v_mov_b32_e32 v19, 0x3d800000
	v_mul_f32_e32 v18, v156, v19
	ds_write_b32 v7, v18 offset:1056
	v_mul_f32_e32 v11, v157, v11
	ds_write_b32 v7, v11 offset:1320
	v_mov_b32_e32 v11, 0x3d800000
	v_mov_b32_e32 v19, 0x3d800000
	v_mul_f32_e32 v18, v158, v19
	ds_write_b32 v7, v18 offset:1584
	v_mul_f32_e32 v10, v159, v11
	s_add_i32 s12, s12, 16
	ds_write_b32 v7, v10 offset:1848
	v_add_u32_e32 v7, 0x840, v7
	s_cmp_eq_u32 s12, 64
	v_lshl_add_u64 v[8:9], v[8:9], 0, 64
	s_cbranch_scc1 .LBB0_1665
	s_branch .LBB0_1668

; __device__ __forceinline__ void cvt_job(const Frame& F, const float* W, int K, int Nsrc, bf16_t* dst, int nrows, int mode, float scale, const float* gain = nullptr) {
;     ...
;     for (int it = F.gw; it < nitems; it += F.NGW) {
;         const int kb = it / nblk, nb = it % nblk, k0 = 64 * kb, n0 = 32 * nb;
;         const int nsrc = map_col(mode, n0 + (lane & 31));
; #pragma unroll 8
;         for (int i = 0; i < 32; ++i) { const int kk = 2 * i + (lane >> 5); scr[kk * 33 + (lane & 31)] = (mode == MAP_ZERO) ? 0.f : W[(size_t)(k0 + kk) * Nsrc + nsrc] * (gain ? scale * gain[k0 + kk] : scale); }
; __device__ __forceinline__ void convert_phase(const Frame& F, int L, int part) {
;     ...
;         cvt_job(F, arg_in(F, 9) + (size_t)j * D * 4096, D, 4096, qkv + (size_t)4096 * D, 4096, MAP_ID, 1.f, g1);
.LBB0_1689:
	s_andn2_b64 vcc, exec, s[36:37]
	s_cbranch_vccnz .Lcvtgm2_ng
	v_lshl_add_u64 v[96:97], v[6:7], 0, s[54:55]
	global_load_dword v152, v[96:97], off
	global_load_dword v153, v[18:19], off offset:-32
	v_lshl_add_u64 v[98:99], v[10:11], 0, s[54:55]
	global_load_dword v154, v[98:99], off
	global_load_dword v155, v[18:19], off offset:-24
	v_lshl_add_u64 v[100:101], v[14:15], 0, s[54:55]
	global_load_dword v156, v[100:101], off
	global_load_dword v157, v[18:19], off offset:-16
	v_lshl_add_u64 v[102:103], v[20:21], 0, s[54:55]
	global_load_dword v158, v[102:103], off
	global_load_dword v159, v[18:19], off offset:-8
	v_lshl_add_u64 v[104:105], v[16:17], 0, s[54:55]
	global_load_dword v160, v[104:105], off
	global_load_dword v161, v[18:19], off
	v_lshl_add_u64 v[106:107], v[12:13], 0, s[54:55]
	global_load_dword v162, v[106:107], off
	global_load_dword v163, v[18:19], off offset:8
	v_lshl_add_u64 v[108:109], v[8:9], 0, s[54:55]
	global_load_dword v164, v[108:109], off
	global_load_dword v165, v[18:19], off offset:16
	v_lshl_add_u64 v[110:111], v[4:5], 0, s[54:55]
	global_load_dword v166, v[110:111], off
	global_load_dword v167, v[18:19], off offset:24
	s_waitcnt vmcnt(0)
	v_cndmask_b32_e64 v40, 0, 1, s[36:37]
	v_mov_b32_e32 v38, 1.0
	v_cmp_ne_u32_e64 s[34:35], 1, v40
	v_mov_b32_e32 v40, 1.0
	v_mul_f32_e32 v39, v152, v153
	ds_write_b32 v37, v39
	v_mul_f32_e32 v38, v154, v155
	ds_write_b32 v37, v38 offset:264
	v_mov_b32_e32 v38, 1.0
	v_mov_b32_e32 v40, 1.0
	v_mul_f32_e32 v39, v156, v157
	ds_write_b32 v37, v39 offset:528
	v_mul_f32_e32 v38, v158, v159
	ds_write_b32 v37, v38 offset:792
	v_mov_b32_e32 v38, 1.0
	v_mov_b32_e32 v40, 1.0
	v_mul_f32_e32 v39, v160, v161
	ds_write_b32 v37, v39 offset:1056
	v_mul_f32_e32 v38, v162, v163
	ds_write_b32 v37, v38 offset:1320
	v_mov_b32_e32 v38, 1.0
	v_mov_b32_e32 v40, 1.0
	v_mul_f32_e32 v39, v164, v165
	ds_write_b32 v37, v39 offset:1584
	s_add_u32 s54, s54, 0x40000
	v_mul_f32_e32 v38, v166, v167
	s_addc_u32 s55, s55, 0
	ds_write_b32 v37, v38 offset:1848
	v_add_u32_e32 v37, 0x840, v37
	s_cmp_eq_u32 s54, 0x100000
	v_lshl_add_u64 v[18:19], v[18:19], 0, 64
	s_cbranch_scc1 .LBB0_1686
	s_branch .LBB0_1689
.Lcvtgm2_ng:
	v_lshl_add_u64 v[96:97], v[6:7], 0, s[54:55]
	global_load_dword v152, v[96:97], off
	v_lshl_add_u64 v[98:99], v[10:11], 0, s[54:55]
	global_load_dword v153, v[98:99], off
	v_lshl_add_u64 v[100:101], v[14:15], 0, s[54:55]
	global_load_dword v154, v[100:101], off
	v_lshl_add_u64 v[102:103], v[20:21], 0, s[54:55]
	global_load_dword v155, v[102:103], off
	v_lshl_add_u64 v[104:105], v[16:17], 0, s[54:55]
	global_load_dword v156, v[104:105], off
	v_lshl_add_u64 v[106:107], v[12:13], 0, s[54:55]
	global_load_dword v157, v[106:107], off
	v_lshl_add_u64 v[108:109], v[8:9], 0, s[54:55]
	global_load_dword v158, v[108:109], off
	v_lshl_add_u64 v[110:111], v[4:5], 0, s[54:55]
	global_load_dword v159, v[110:111], off
	s_waitcnt vmcnt(0)
	v_cndmask_b32_e64 v40, 0, 1, s[36:37]
	v_mov_b32_e32 v38, 1.0
	v_cmp_ne_u32_e64 s[34:35], 1, v40
	v_mov_b32_e32 v40, 1.0
	v_mul_f32_e32 v39, v152, v40
	ds_write_b32 v37, v39
	v_mul_f32_e32 v38, v153, v38
	ds_write_b32 v37, v38 offset:264
	v_mov_b32_e32 v38, 1.0
	v_mov_b32_e32 v40, 1.0
	v_mul_f32_e32 v39, v154, v40
	ds_write_b32 v37, v39 offset:528
	v_mul_f32_e32 v38, v155, v38
	ds_write_b32 v37, v38 offset:792
	v_mov_b32_e32 v38, 1.0
	v_mov_b32_e32 v40, 1.0
	v_mul_f32_e32 v39, v156, v40
	ds_write_b32 v37, v39 offset:1056
	v_mul_f32_e32 v38, v157, v38
	ds_write_b32 v37, v38 offset:1320
	v_mov_b32_e32 v38, 1.0
	v_mov_b32_e32 v40, 1.0
	v_mul_f32_e32 v39, v158, v40
	ds_write_b32 v37, v39 offset:1584
	s_add_u32 s54, s54, 0x40000
	v_mul_f32_e32 v38, v159, v38
	s_addc_u32 s55, s55, 0
	ds_write_b32 v37, v38 offset:1848
	v_add_u32_e32 v37, 0x840, v37
	s_cmp_eq_u32 s54, 0x100000
	v_lshl_add_u64 v[18:19], v[18:19], 0, 64
	s_cbranch_scc1 .LBB0_1686
	s_branch .LBB0_1689

; __device__ __forceinline__ void cvt_job(const Frame& F, const float* W, int K, int Nsrc, bf16_t* dst, int nrows, int mode, float scale, const float* gain = nullptr) {
;     ...
;     for (int it = F.gw; it < nitems; it += F.NGW) {
;         const int kb = it / nblk, nb = it % nblk, k0 = 64 * kb, n0 = 32 * nb;
;         const int nsrc = map_col(mode, n0 + (lane & 31));
; #pragma unroll 8
;         for (int i = 0; i < 32; ++i) { const int kk = 2 * i + (lane >> 5); scr[kk * 33 + (lane & 31)] = (mode == MAP_ZERO) ? 0.f : W[(size_t)(k0 + kk) * Nsrc + nsrc] * (gain ? scale * gain[k0 + kk] : scale); }
; __device__ __forceinline__ void convert_phase(const Frame& F, int L, int part) {
;     ...
;         cvt_job(F, arg_in(F, 10) + (size_t)j * D * 4096, D, 4096, (bf16_t*)(wr + W_RG), 4096, MAP_ID, 1.f, g1);
.LBB0_1710:
	s_andn2_b64 vcc, exec, s[30:31]
	s_cbranch_vccnz .Lcvtgm3_ng
	v_lshl_add_u64 v[96:97], v[6:7], 0, s[52:53]
	global_load_dword v152, v[96:97], off
	global_load_dword v153, v[18:19], off offset:-32
	v_lshl_add_u64 v[98:99], v[10:11], 0, s[52:53]
	global_load_dword v154, v[98:99], off
	global_load_dword v155, v[18:19], off offset:-24
	v_lshl_add_u64 v[100:101], v[14:15], 0, s[52:53]
	global_load_dword v156, v[100:101], off
	global_load_dword v157, v[18:19], off offset:-16
	v_lshl_add_u64 v[102:103], v[20:21], 0, s[52:53]
	global_load_dword v158, v[102:103], off
	global_load_dword v159, v[18:19], off offset:-8
	v_lshl_add_u64 v[104:105], v[16:17], 0, s[52:53]
	global_load_dword v160, v[104:105], off
	global_load_dword v161, v[18:19], off
	v_lshl_add_u64 v[106:107], v[12:13], 0, s[52:53]
	global_load_dword v162, v[106:107], off
	global_load_dword v163, v[18:19], off offset:8
	v_lshl_add_u64 v[108:109], v[8:9], 0, s[52:53]
	global_load_dword v164, v[108:109], off
	global_load_dword v165, v[18:19], off offset:16
	v_lshl_add_u64 v[110:111], v[4:5], 0, s[52:53]
	global_load_dword v166, v[110:111], off
	global_load_dword v167, v[18:19], off offset:24
	s_waitcnt vmcnt(0)
	v_cndmask_b32_e64 v40, 0, 1, s[30:31]
	v_mov_b32_e32 v38, 1.0
	v_cmp_ne_u32_e64 s[36:37], 1, v40
	v_mov_b32_e32 v40, 1.0
	v_mul_f32_e32 v39, v152, v153
	ds_write_b32 v37, v39
	v_mul_f32_e32 v38, v154, v155
	ds_write_b32 v37, v38 offset:264
	v_mov_b32_e32 v38, 1.0
	v_mov_b32_e32 v40, 1.0
	v_mul_f32_e32 v39, v156, v157
	ds_write_b32 v37, v39 offset:528
	v_mul_f32_e32 v38, v158, v159
	ds_write_b32 v37, v38 offset:792
	v_mov_b32_e32 v38, 1.0
	v_mov_b32_e32 v40, 1.0
	v_mul_f32_e32 v39, v160, v161
	ds_write_b32 v37, v39 offset:1056
	v_mul_f32_e32 v38, v162, v163
	ds_write_b32 v37, v38 offset:1320
	v_mov_b32_e32 v38, 1.0
	v_mov_b32_e32 v40, 1.0
	v_mul_f32_e32 v39, v164, v165
	ds_write_b32 v37, v39 offset:1584
	s_add_u32 s52, s52, 0x40000
	v_mul_f32_e32 v38, v166, v167
	s_addc_u32 s53, s53, 0
	ds_write_b32 v37, v38 offset:1848
	v_add_u32_e32 v37, 0x840, v37
	s_cmp_eq_u32 s52, 0x100000
	v_lshl_add_u64 v[18:19], v[18:19], 0, 64
	s_cbranch_scc1 .LBB0_1707
	s_branch .LBB0_1710
.Lcvtgm3_ng:
	v_lshl_add_u64 v[96:97], v[6:7], 0, s[52:53]
	global_load_dword v152, v[96:97], off
	v_lshl_add_u64 v[98:99], v[10:11], 0, s[52:53]
	global_load_dword v153, v[98:99], off
	v_lshl_add_u64 v[100:101], v[14:15], 0, s[52:53]
	global_load_dword v154, v[100:101], off
	v_lshl_add_u64 v[102:103], v[20:21], 0, s[52:53]
	global_load_dword v155, v[102:103], off
	v_lshl_add_u64 v[104:105], v[16:17], 0, s[52:53]
	global_load_dword v156, v[104:105], off
	v_lshl_add_u64 v[106:107], v[12:13], 0, s[52:53]
	global_load_dword v157, v[106:107], off
	v_lshl_add_u64 v[108:109], v[8:9], 0, s[52:53]
	global_load_dword v158, v[108:109], off
	v_lshl_add_u64 v[110:111], v[4:5], 0, s[52:53]
	global_load_dword v159, v[110:111], off
	s_waitcnt vmcnt(0)
	v_cndmask_b32_e64 v40, 0, 1, s[30:31]
	v_mov_b32_e32 v38, 1.0
	v_cmp_ne_u32_e64 s[36:37], 1, v40
	v_mov_b32_e32 v40, 1.0
	v_mul_f32_e32 v39, v152, v40
	ds_write_b32 v37, v39
	v_mul_f32_e32 v38, v153, v38
	ds_write_b32 v37, v38 offset:264
	v_mov_b32_e32 v38, 1.0
	v_mov_b32_e32 v40, 1.0
	v_mul_f32_e32 v39, v154, v40
	ds_write_b32 v37, v39 offset:528
	v_mul_f32_e32 v38, v155, v38
	ds_write_b32 v37, v38 offset:792
	v_mov_b32_e32 v38, 1.0
	v_mov_b32_e32 v40, 1.0
	v_mul_f32_e32 v39, v156, v40
	ds_write_b32 v37, v39 offset:1056
	v_mul_f32_e32 v38, v157, v38
	ds_write_b32 v37, v38 offset:1320
	v_mov_b32_e32 v38, 1.0
	v_mov_b32_e32 v40, 1.0
	v_mul_f32_e32 v39, v158, v40
	ds_write_b32 v37, v39 offset:1584
	s_add_u32 s52, s52, 0x40000
	v_mul_f32_e32 v38, v159, v38
	s_addc_u32 s53, s53, 0
	ds_write_b32 v37, v38 offset:1848
	v_add_u32_e32 v37, 0x840, v37
	s_cmp_eq_u32 s52, 0x100000
	v_lshl_add_u64 v[18:19], v[18:19], 0, 64
	s_cbranch_scc1 .LBB0_1707
	s_branch .LBB0_1710
